# spin loops (epilogue arrival counter, grid barrier) poll without s_sleep
# baseline (speedup 1.0000x reference)
;   __device__ __forceinline__ void operator()(f32x4 (&acc)[2][2][4][2], int pm, int pn, int wr_, int wc_, int fr_, int fq_, bf16_t* shm, int tid) const {
;     ...
;     if (tid == 0) {
;       __hip_atomic_fetch_add(cnt + pm * 16, 1u, __ATOMIC_RELAXED, __HIP_MEMORY_SCOPE_AGENT);
;       unsigned sp = 0;
;       while (__hip_atomic_load(cnt + pm * 16, __ATOMIC_RELAXED, __HIP_MEMORY_SCOPE_AGENT) < 4u * gen) { __builtin_amdgcn_s_sleep(1); if (++sp > (1u << 22)) break; }
;     }
.LBB0_223:
	global_load_dword v130, v1, s[14:15] sc1
	s_mov_b64 s[40:41], -1
	s_waitcnt vmcnt(0)
	v_cmp_le_u32_e32 vcc, s22, v130
	s_cbranch_vccnz .LBB0_222
	global_load_dword v130, v1, s[14:15] sc1
	s_waitcnt vmcnt(0)
	v_cmp_gt_u32_e32 vcc, s22, v130
	s_cbranch_vccz .LBB0_222
	global_load_dword v130, v1, s[14:15] sc1
	s_waitcnt vmcnt(0)
	v_cmp_gt_u32_e32 vcc, s22, v130
	s_cbranch_vccz .LBB0_222
	global_load_dword v130, v1, s[14:15] sc1
	s_waitcnt vmcnt(0)
	v_cmp_gt_u32_e32 vcc, s22, v130
	s_cbranch_vccz .LBB0_222
	global_load_dword v130, v1, s[14:15] sc1
	s_waitcnt vmcnt(0)
	v_cmp_gt_u32_e32 vcc, s22, v130
	s_cbranch_vccz .LBB0_222
	s_add_i32 s11, s11, -5
	s_cmp_eq_u32 s11, 0
	s_cselect_b64 s[40:41], -1, 0
	s_branch .LBB0_222

;   __device__ __forceinline__ void operator()(f32x4 (&acc)[2][2][4][2], int pm, int pn, int wr_, int wc_, int fr_, int fq_, bf16_t* shm, int tid) const {
;     ...
;     if (tid == 0) {
;       __hip_atomic_fetch_add(cnt + pm * 16, 1u, __ATOMIC_RELAXED, __HIP_MEMORY_SCOPE_AGENT);
;       unsigned sp = 0;
;       while (__hip_atomic_load(cnt + pm * 16, __ATOMIC_RELAXED, __HIP_MEMORY_SCOPE_AGENT) < 4u * gen) { __builtin_amdgcn_s_sleep(1); if (++sp > (1u << 22)) break; }
;     }
.LBB0_570:
	global_load_dword v130, v1, s[12:13] sc1
	s_mov_b64 s[14:15], -1
	s_waitcnt vmcnt(0)
	v_cmp_le_u32_e32 vcc, s21, v130
	s_cbranch_vccnz .LBB0_569
	global_load_dword v130, v1, s[12:13] sc1
	s_waitcnt vmcnt(0)
	v_cmp_gt_u32_e32 vcc, s21, v130
	s_cbranch_vccz .LBB0_569
	global_load_dword v130, v1, s[12:13] sc1
	s_waitcnt vmcnt(0)
	v_cmp_gt_u32_e32 vcc, s21, v130
	s_cbranch_vccz .LBB0_569
	global_load_dword v130, v1, s[12:13] sc1
	s_waitcnt vmcnt(0)
	v_cmp_gt_u32_e32 vcc, s21, v130
	s_cbranch_vccz .LBB0_569
	global_load_dword v130, v1, s[12:13] sc1
	s_waitcnt vmcnt(0)
	v_cmp_gt_u32_e32 vcc, s21, v130
	s_cbranch_vccz .LBB0_569
	s_add_i32 s5, s5, -5
	s_cmp_eq_u32 s5, 0
	s_cselect_b64 s[14:15], -1, 0
	s_branch .LBB0_569

; __device__ __forceinline__ unsigned xb_ld(unsigned* p)              { return __hip_atomic_load(p, __ATOMIC_RELAXED, __HIP_MEMORY_SCOPE_AGENT); }
; __device__ __forceinline__ void xcd_barrier_complete(unsigned* bar, unsigned x, unsigned& nloc, unsigned& nx) {
;     ...
;   for (;;) {
;     sum = 0u; cnt = 0u; mine = 0u;
; #pragma unroll
;     for (unsigned j = 0; j < 16; ++j) { const unsigned c = xb_ld(&bar[XB_XCNT(j)]); sum += c; cnt += (c > 0u) ? 1u : 0u; mine = (j == x) ? c : mine; }
;     if (sum == G) break;
;     __builtin_amdgcn_s_sleep(1);
;     if ((++sp & 255u) == 0u) { if (xb_ld(&bar[XB_TMO])) break; if (sp > XB_SPIN_CAP) { atomicAdd(&bar[XB_TMO], 1u); break; } }
;   }
.LBB0_1000:
	v_readlane_b32 s12, v251, 49
	v_readlane_b32 s16, v251, 53
	v_readlane_b32 s17, v251, 54
	s_nop 4
	global_load_dword v11, v1, s[16:17] offset:1024 sc1
	global_load_dword v0, v1, s[16:17] offset:1280 sc1
	s_waitcnt lgkmcnt(0)
	global_load_dword v2, v1, s[16:17] offset:1536 sc1
	global_load_dword v3, v1, s[16:17] offset:1792 sc1
	global_load_dword v4, v1, s[16:17] offset:2048 sc1
	global_load_dword v5, v1, s[16:17] offset:2304 sc1
	global_load_dword v6, v1, s[16:17] offset:2560 sc1
	global_load_dword v7, v1, s[16:17] offset:2816 sc1
	global_load_dword v8, v1, s[16:17] offset:3072 sc1
	global_load_dword v9, v1, s[16:17] offset:3328 sc1
	global_load_dword v10, v1, s[16:17] offset:3584 sc1
	global_load_dword v12, v1, s[16:17] offset:3840 sc1
	global_load_dword v13, v1, s[24:25] sc1
	global_load_dword v14, v1, s[28:29] sc1
	global_load_dword v15, v1, s[30:31] sc1
	global_load_dword v16, v1, s[60:61] sc1
	s_mov_b64 s[4:5], -1
	s_mov_b64 s[6:7], -1
	v_readlane_b32 s13, v251, 50
	v_readlane_b32 s14, v251, 51
	v_readlane_b32 s15, v251, 52
	v_readlane_b32 s18, v251, 55
	v_readlane_b32 s19, v251, 56
	s_waitcnt vmcnt(14)
	v_add_u32_e32 v17, v0, v11
	s_waitcnt vmcnt(13)
	v_add_u32_e32 v17, v17, v2
	s_waitcnt vmcnt(12)
	v_add_u32_e32 v17, v17, v3
	s_waitcnt vmcnt(11)
	v_add_u32_e32 v17, v17, v4
	s_waitcnt vmcnt(10)
	v_add_u32_e32 v17, v17, v5
	s_waitcnt vmcnt(9)
	v_add_u32_e32 v17, v17, v6
	s_waitcnt vmcnt(8)
	v_add_u32_e32 v17, v17, v7
	s_waitcnt vmcnt(7)
	v_add_u32_e32 v17, v17, v8
	s_waitcnt vmcnt(6)
	v_add_u32_e32 v17, v17, v9
	s_waitcnt vmcnt(5)
	v_add_u32_e32 v17, v17, v10
	s_waitcnt vmcnt(4)
	v_add_u32_e32 v17, v17, v12
	s_waitcnt vmcnt(3)
	v_add_u32_e32 v17, v17, v13
	s_waitcnt vmcnt(2)
	v_add_u32_e32 v17, v17, v14
	s_waitcnt vmcnt(1)
	v_add_u32_e32 v17, v17, v15
	s_waitcnt vmcnt(0)
	v_add_u32_e32 v17, v17, v16
	v_cmp_eq_u32_e32 vcc, s21, v17
	s_cbranch_vccnz .LBB0_999
	s_and_b32 s4, s10, 0xff
	s_cmp_eq_u32 s4, 0
	s_mov_b64 s[4:5], -1
	s_mov_b64 s[8:9], -1
	s_cbranch_scc1 .LBB0_1004
	s_and_b64 vcc, exec, s[8:9]
	s_cbranch_vccz .LBB0_999

; __device__ __forceinline__ unsigned xb_ld(unsigned* p)              { return __hip_atomic_load(p, __ATOMIC_RELAXED, __HIP_MEMORY_SCOPE_AGENT); }
; __device__ __forceinline__ unsigned xb_add(unsigned* p, unsigned v) { return __hip_atomic_fetch_add(p, v, __ATOMIC_RELAXED, __HIP_MEMORY_SCOPE_AGENT); }
; #define XB_SPIN(cond, bar) do { unsigned _sp = 0; while (cond) { __builtin_amdgcn_s_sleep(1); \
;     if ((++_sp & 255u) == 0u) { if (xb_ld(&(bar)[XB_TMO])) break; if (_sp > XB_SPIN_CAP) { atomicAdd(&(bar)[XB_TMO], 1u); break; } } } } while (0)
; __device__ __forceinline__ void xcd_barrier(unsigned* bar_, volatile LAS unsigned* st_, int tid) {
;     ...
;       const unsigned og = xb_add(&bar[XB_TOP], 1u);
;       const unsigned tg = og / nx;
;       if (og + 1u == (tg + 1u) * nx) xb_add(&bar[XB_TOPGEN], 1u);
;       else XB_SPIN(xb_ld(&bar[XB_TOPGEN]) == tg, bar);
.LBB0_1018:
	s_and_b32 s17, s2, 0xff
	s_mov_b64 s[40:41], -1
	s_cmp_lg_u32 s17, 0
	s_mov_b64 s[44:45], -1
	s_cbranch_scc0 .LBB0_1021
	s_and_b64 vcc, exec, s[44:45]
	s_cbranch_vccz .LBB0_1017

; __device__ __forceinline__ unsigned xb_ld(unsigned* p)              { return __hip_atomic_load(p, __ATOMIC_RELAXED, __HIP_MEMORY_SCOPE_AGENT); }
; #define XB_SPIN(cond, bar) do { unsigned _sp = 0; while (cond) { __builtin_amdgcn_s_sleep(1); \
;     if ((++_sp & 255u) == 0u) { if (xb_ld(&(bar)[XB_TMO])) break; if (_sp > XB_SPIN_CAP) { atomicAdd(&(bar)[XB_TMO], 1u); break; } } } } while (0)
; __device__ __forceinline__ void xcd_barrier(unsigned* bar_, volatile LAS unsigned* st_, int tid) {
;     ...
;     } else {
;       XB_SPIN(xb_ld(&bar[XB_XGEN(b.x)]) == gen, bar);
.LBB0_1035:
	s_and_b32 s17, s2, 0xff
	s_mov_b64 s[14:15], -1
	s_cmp_lg_u32 s17, 0
	s_mov_b64 s[42:43], -1
	s_cbranch_scc0 .LBB0_1038
	s_and_b64 vcc, exec, s[42:43]
	s_cbranch_vccz .LBB0_1034
